# accumulator zeroing at each GEMM unit start with 64-bit moves (64 instead of 128 VALU ops per unit)
# speedup vs baseline: 1.0140x; 1.0053x over previous
; template <class Epi, class Sched, bool ALIGN_EPI = false, bool SP2 = false>
; __device__ __forceinline__ void gemm_phase(PG8_LAS unsigned char* lds, const Gemm g, const Sched& S, const Epi& E) {
;     ...
;         const char* nA = has_next ? (const char*)g.A + (size_t)nxt.pm * tstep : cA; const char* nB = has_next ? (const char*)g.Bt + (size_t)nxt.pn * tstep : cB;
;         for (int t = 0; t < nt; t += 2) {
;             const bool last = (t == nt - 2);
;             const char* a1 = cA + (size_t)(t + 1) * kstep;
;             const char* a2 = last ? nA : cA + (size_t)(t + 2) * kstep; const char* b2 = last ? nB : cB + (size_t)(t + 2) * kstep;
;     ...
; #pragma unroll
;         for (int a = 0; a < 2; ++a)
; #pragma unroll
;             for (int b = 0; b < 2; ++b)
; #pragma unroll
;                 for (int m = 0; m < 4; ++m)
; #pragma unroll
;                     for (int n = 0; n < 2; ++n) acc[a][b][m][n] = (f32x4){0.f, 0.f, 0.f, 0.f};
.LBB0_189:
	s_ashr_i32 s75, s74, 31
	s_lshl_b64 s[2:3], s[74:75], 19
	s_add_u32 s80, s64, s2
	s_addc_u32 s81, s65, s3
	s_and_b64 s[2:3], s[0:1], exec
	s_cselect_b32 s2, s81, s7
	s_cselect_b32 s3, s80, s6
	s_ashr_i32 s93, s92, 31
	s_lshl_b64 s[8:9], s[92:93], 19
	s_add_u32 s82, s84, s8
	s_addc_u32 s83, s85, s9
	s_and_b64 s[8:9], s[0:1], exec
	s_cselect_b32 s5, s83, s35
	s_cselect_b32 s8, s82, s34
	s_add_u32 s6, s6, 0x40080
	s_addc_u32 s7, s7, 0
	s_add_u32 s9, s34, 0x100
	v_mov_b64_e32 v[2:3], 0
	s_addc_u32 s33, s35, 0
	s_mov_b32 s46, -2
	v_mov_b64_e32 v[4:5], 0
	v_mov_b64_e32 v[6:7], 0
	v_mov_b64_e32 v[8:9], 0
	v_mov_b64_e32 v[14:15], 0
	v_mov_b64_e32 v[16:17], 0
	v_mov_b64_e32 v[22:23], 0
	v_mov_b64_e32 v[24:25], 0
	v_mov_b64_e32 v[30:31], 0
	v_mov_b64_e32 v[32:33], 0
	v_mov_b64_e32 v[38:39], 0
	v_mov_b64_e32 v[40:41], 0
	v_mov_b64_e32 v[46:47], 0
	v_mov_b64_e32 v[48:49], 0
	s_waitcnt lgkmcnt(0)
	v_mov_b64_e32 v[54:55], 0
	v_mov_b64_e32 v[56:57], 0
	v_mov_b64_e32 v[10:11], 0
	v_mov_b64_e32 v[12:13], 0
	v_mov_b64_e32 v[18:19], 0
	v_mov_b64_e32 v[20:21], 0
	v_mov_b64_e32 v[26:27], 0
	v_mov_b64_e32 v[28:29], 0
	v_mov_b64_e32 v[34:35], 0
	v_mov_b64_e32 v[36:37], 0
	v_mov_b64_e32 v[42:43], 0
	v_mov_b64_e32 v[44:45], 0
	v_mov_b64_e32 v[50:51], 0
	v_mov_b64_e32 v[52:53], 0
	v_mov_b64_e32 v[58:59], 0
	v_mov_b64_e32 v[60:61], 0
	v_mov_b64_e32 v[62:63], 0
	v_mov_b64_e32 v[64:65], 0
	v_mov_b64_e32 v[66:67], 0
	v_mov_b64_e32 v[68:69], 0
	v_mov_b64_e32 v[70:71], 0
	v_mov_b64_e32 v[72:73], 0
	v_mov_b64_e32 v[78:79], 0
	v_mov_b64_e32 v[80:81], 0
	v_mov_b64_e32 v[86:87], 0
	v_mov_b64_e32 v[88:89], 0
	v_mov_b64_e32 v[94:95], 0
	v_mov_b64_e32 v[96:97], 0
	v_mov_b64_e32 v[102:103], 0
	v_mov_b64_e32 v[104:105], 0
	v_mov_b64_e32 v[110:111], 0
	v_mov_b64_e32 v[112:113], 0
	v_mov_b64_e32 v[118:119], 0
	v_mov_b64_e32 v[120:121], 0
	v_mov_b64_e32 v[74:75], 0
	v_mov_b64_e32 v[76:77], 0
	v_mov_b64_e32 v[82:83], 0
	v_mov_b64_e32 v[84:85], 0
	v_mov_b64_e32 v[90:91], 0
	v_mov_b64_e32 v[92:93], 0
	v_mov_b64_e32 v[98:99], 0
	v_mov_b64_e32 v[100:101], 0
	v_mov_b64_e32 v[106:107], 0
	v_mov_b64_e32 v[108:109], 0
	v_mov_b64_e32 v[114:115], 0
	v_mov_b64_e32 v[116:117], 0
	v_mov_b64_e32 v[122:123], 0
	v_mov_b64_e32 v[124:125], 0
	v_mov_b64_e32 v[126:127], 0
	v_mov_b64_e32 v[128:129], 0

; template <class Epi, class Sched, bool ALIGN_EPI = false, bool SP2 = false>
; __device__ __forceinline__ void gemm_phase(PG8_LAS unsigned char* lds, const Gemm g, const Sched& S, const Epi& E) {
;     ...
;         const char* nA = has_next ? (const char*)g.A + (size_t)nxt.pm * tstep : cA; const char* nB = has_next ? (const char*)g.Bt + (size_t)nxt.pn * tstep : cB;
;         for (int t = 0; t < nt; t += 2) {
;             const bool last = (t == nt - 2);
;             const char* a1 = cA + (size_t)(t + 1) * kstep;
;             const char* a2 = last ? nA : cA + (size_t)(t + 2) * kstep; const char* b2 = last ? nB : cB + (size_t)(t + 2) * kstep;
;     ...
; #pragma unroll
;         for (int a = 0; a < 2; ++a)
; #pragma unroll
;             for (int b = 0; b < 2; ++b)
; #pragma unroll
;                 for (int m = 0; m < 4; ++m)
; #pragma unroll
;                     for (int n = 0; n < 2; ++n) acc[a][b][m][n] = (f32x4){0.f, 0.f, 0.f, 0.f};
.LBB0_327:
	s_ashr_i32 s21, s20, 31
	s_lshl_b64 s[2:3], s[20:21], 19
	s_add_u32 s22, s55, s2
	s_addc_u32 s23, s56, s3
	s_and_b64 s[2:3], s[12:13], exec
	s_cselect_b32 s2, s23, s27
	s_cselect_b32 s3, s22, s26
	s_ashr_i32 s19, s18, 31
	s_lshl_b64 s[24:25], s[18:19], 19
	s_add_u32 s24, s74, s24
	s_addc_u32 s25, s75, s25
	s_and_b64 s[30:31], s[12:13], exec
	s_cselect_b32 s19, s25, s29
	s_cselect_b32 s21, s24, s28
	s_add_u32 s26, s26, 0x40080
	s_addc_u32 s27, s27, 0
	s_add_u32 s47, s28, 0x100
	v_mov_b64_e32 v[2:3], 0
	s_addc_u32 s48, s29, 0
	s_mov_b32 s49, -2
	v_mov_b64_e32 v[4:5], 0
	v_mov_b64_e32 v[6:7], 0
	v_mov_b64_e32 v[8:9], 0
	v_mov_b64_e32 v[10:11], 0
	v_mov_b64_e32 v[12:13], 0
	v_mov_b64_e32 v[18:19], 0
	v_mov_b64_e32 v[20:21], 0
	v_mov_b64_e32 v[26:27], 0
	v_mov_b64_e32 v[28:29], 0
	v_mov_b64_e32 v[34:35], 0
	v_mov_b64_e32 v[36:37], 0
	v_mov_b64_e32 v[42:43], 0
	v_mov_b64_e32 v[44:45], 0
	v_mov_b64_e32 v[50:51], 0
	v_mov_b64_e32 v[52:53], 0
	v_mov_b64_e32 v[14:15], 0
	v_mov_b64_e32 v[16:17], 0
	v_mov_b64_e32 v[22:23], 0
	v_mov_b64_e32 v[24:25], 0
	v_mov_b64_e32 v[30:31], 0
	v_mov_b64_e32 v[32:33], 0
	v_mov_b64_e32 v[38:39], 0
	v_mov_b64_e32 v[40:41], 0
	v_mov_b64_e32 v[46:47], 0
	v_mov_b64_e32 v[48:49], 0
	s_waitcnt lgkmcnt(0)
	v_mov_b64_e32 v[54:55], 0
	v_mov_b64_e32 v[56:57], 0
	v_mov_b64_e32 v[58:59], 0
	v_mov_b64_e32 v[60:61], 0
	v_mov_b64_e32 v[62:63], 0
	v_mov_b64_e32 v[64:65], 0
	v_mov_b64_e32 v[66:67], 0
	v_mov_b64_e32 v[68:69], 0
	v_mov_b64_e32 v[70:71], 0
	v_mov_b64_e32 v[72:73], 0
	v_mov_b64_e32 v[78:79], 0
	v_mov_b64_e32 v[80:81], 0
	v_mov_b64_e32 v[86:87], 0
	v_mov_b64_e32 v[88:89], 0
	v_mov_b64_e32 v[94:95], 0
	v_mov_b64_e32 v[96:97], 0
	v_mov_b64_e32 v[102:103], 0
	v_mov_b64_e32 v[104:105], 0
	v_mov_b64_e32 v[110:111], 0
	v_mov_b64_e32 v[112:113], 0
	v_mov_b64_e32 v[118:119], 0
	v_mov_b64_e32 v[120:121], 0
	v_mov_b64_e32 v[74:75], 0
	v_mov_b64_e32 v[76:77], 0
	v_mov_b64_e32 v[82:83], 0
	v_mov_b64_e32 v[84:85], 0
	v_mov_b64_e32 v[90:91], 0
	v_mov_b64_e32 v[92:93], 0
	v_mov_b64_e32 v[98:99], 0
	v_mov_b64_e32 v[100:101], 0
	v_mov_b64_e32 v[106:107], 0
	v_mov_b64_e32 v[108:109], 0
	v_mov_b64_e32 v[114:115], 0
	v_mov_b64_e32 v[116:117], 0
	v_mov_b64_e32 v[122:123], 0
	v_mov_b64_e32 v[124:125], 0
	v_mov_b64_e32 v[126:127], 0
	v_mov_b64_e32 v[128:129], 0

; template <class Epi, class Sched, bool ALIGN_EPI = false, bool SP2 = false>
; __device__ __forceinline__ void gemm_phase(PG8_LAS unsigned char* lds, const Gemm g, const Sched& S, const Epi& E) {
;     ...
;         const char* nA = has_next ? (const char*)g.A + (size_t)nxt.pm * tstep : cA; const char* nB = has_next ? (const char*)g.Bt + (size_t)nxt.pn * tstep : cB;
;         for (int t = 0; t < nt; t += 2) {
;             const bool last = (t == nt - 2);
;             const char* a1 = cA + (size_t)(t + 1) * kstep;
;             const char* a2 = last ? nA : cA + (size_t)(t + 2) * kstep; const char* b2 = last ? nB : cB + (size_t)(t + 2) * kstep;
;     ...
; #pragma unroll
;         for (int a = 0; a < 2; ++a)
; #pragma unroll
;             for (int b = 0; b < 2; ++b)
; #pragma unroll
;                 for (int m = 0; m < 4; ++m)
; #pragma unroll
;                     for (int n = 0; n < 2; ++n) acc[a][b][m][n] = (f32x4){0.f, 0.f, 0.f, 0.f};
.LBB0_770:
	s_ashr_i32 s19, s18, 31
	s_lshl_b64 s[2:3], s[18:19], 19
	s_add_u32 s24, s38, s2
	s_addc_u32 s25, s39, s3
	s_and_b64 s[2:3], s[4:5], exec
	s_cselect_b32 s2, s25, s31
	s_cselect_b32 s3, s24, s30
	s_ashr_i32 s17, s16, 31
	s_lshl_b64 s[26:27], s[16:17], 19
	s_add_u32 s26, s94, s26
	s_addc_u32 s27, s95, s27
	s_and_b64 s[40:41], s[4:5], exec
	s_cselect_b32 s17, s27, s35
	s_cselect_b32 s19, s26, s34
	s_add_u32 s30, s30, 0x40080
	s_addc_u32 s31, s31, 0
	s_add_u32 s29, s34, 0x100
	v_mov_b64_e32 v[2:3], 0
	s_addc_u32 s54, s35, 0
	s_mov_b32 s55, -2
	v_mov_b64_e32 v[4:5], 0
	v_mov_b64_e32 v[6:7], 0
	v_mov_b64_e32 v[8:9], 0
	v_mov_b64_e32 v[18:19], 0
	v_mov_b64_e32 v[20:21], 0
	v_mov_b64_e32 v[22:23], 0
	v_mov_b64_e32 v[24:25], 0
	v_mov_b64_e32 v[34:35], 0
	v_mov_b64_e32 v[36:37], 0
	v_mov_b64_e32 v[38:39], 0
	v_mov_b64_e32 v[40:41], 0
	v_mov_b64_e32 v[50:51], 0
	v_mov_b64_e32 v[52:53], 0
	s_waitcnt lgkmcnt(0)
	v_mov_b64_e32 v[54:55], 0
	v_mov_b64_e32 v[56:57], 0
	v_mov_b64_e32 v[10:11], 0
	v_mov_b64_e32 v[12:13], 0
	v_mov_b64_e32 v[14:15], 0
	v_mov_b64_e32 v[16:17], 0
	v_mov_b64_e32 v[26:27], 0
	v_mov_b64_e32 v[28:29], 0
	v_mov_b64_e32 v[30:31], 0
	v_mov_b64_e32 v[32:33], 0
	v_mov_b64_e32 v[42:43], 0
	v_mov_b64_e32 v[44:45], 0
	v_mov_b64_e32 v[46:47], 0
	v_mov_b64_e32 v[48:49], 0
	v_mov_b64_e32 v[58:59], 0
	v_mov_b64_e32 v[60:61], 0
	v_mov_b64_e32 v[62:63], 0
	v_mov_b64_e32 v[64:65], 0
	v_mov_b64_e32 v[66:67], 0
	v_mov_b64_e32 v[68:69], 0
	v_mov_b64_e32 v[70:71], 0
	v_mov_b64_e32 v[72:73], 0
	v_mov_b64_e32 v[82:83], 0
	v_mov_b64_e32 v[84:85], 0
	v_mov_b64_e32 v[86:87], 0
	v_mov_b64_e32 v[88:89], 0
	v_mov_b64_e32 v[98:99], 0
	v_mov_b64_e32 v[100:101], 0
	v_mov_b64_e32 v[102:103], 0
	v_mov_b64_e32 v[104:105], 0
	v_mov_b64_e32 v[122:123], 0
	v_mov_b64_e32 v[124:125], 0
	v_mov_b64_e32 v[134:135], 0
	v_mov_b64_e32 v[136:137], 0
	v_mov_b64_e32 v[74:75], 0
	v_mov_b64_e32 v[76:77], 0
	v_mov_b64_e32 v[78:79], 0
	v_mov_b64_e32 v[80:81], 0
	v_mov_b64_e32 v[90:91], 0
	v_mov_b64_e32 v[92:93], 0
	v_mov_b64_e32 v[94:95], 0
	v_mov_b64_e32 v[96:97], 0
	v_mov_b64_e32 v[106:107], 0
	v_mov_b64_e32 v[108:109], 0
	v_mov_b64_e32 v[110:111], 0
	v_mov_b64_e32 v[112:113], 0
	v_mov_b64_e32 v[150:151], 0
	v_mov_b64_e32 v[152:153], 0
	v_mov_b64_e32 v[158:159], 0
	v_mov_b64_e32 v[160:161], 0

; template <class Epi, class Sched, bool ALIGN_EPI = false, bool SP2 = false>
; __device__ __forceinline__ void gemm_phase(PG8_LAS unsigned char* lds, const Gemm g, const Sched& S, const Epi& E) {
;     ...
;         const char* nA = has_next ? (const char*)g.A + (size_t)nxt.pm * tstep : cA; const char* nB = has_next ? (const char*)g.Bt + (size_t)nxt.pn * tstep : cB;
;         for (int t = 0; t < nt; t += 2) {
;             const bool last = (t == nt - 2);
;             const char* a1 = cA + (size_t)(t + 1) * kstep;
;             const char* a2 = last ? nA : cA + (size_t)(t + 2) * kstep; const char* b2 = last ? nB : cB + (size_t)(t + 2) * kstep;
;     ...
; #pragma unroll
;         for (int a = 0; a < 2; ++a)
; #pragma unroll
;             for (int b = 0; b < 2; ++b)
; #pragma unroll
;                 for (int m = 0; m < 4; ++m)
; #pragma unroll
;                     for (int n = 0; n < 2; ++n) acc[a][b][m][n] = (f32x4){0.f, 0.f, 0.f, 0.f};
.LBB0_884:
	s_ashr_i32 s65, s64, 31
	s_lshl_b64 s[2:3], s[64:65], 19
	v_readlane_b32 s42, v254, 60
	v_readlane_b32 s43, v254, 61
	s_add_u32 s66, s42, s2
	s_addc_u32 s67, s43, s3
	s_and_b64 s[2:3], s[8:9], exec
	s_cselect_b32 s2, s67, s71
	s_cselect_b32 s3, s66, s70
	s_ashr_i32 s61, s60, 31
	s_lshl_b64 s[42:43], s[60:61], 19
	v_readlane_b32 s68, v254, 40
	v_readlane_b32 s69, v254, 41
	s_add_u32 s68, s68, s42
	s_addc_u32 s69, s69, s43
	s_and_b64 s[42:43], s[8:9], exec
	s_cselect_b32 s29, s69, s35
	s_cselect_b32 s61, s68, s34
	s_add_u32 s70, s70, 0x40080
	s_addc_u32 s71, s71, 0
	s_add_u32 s65, s34, 0x100
	v_mov_b64_e32 v[2:3], 0
	s_addc_u32 s72, s35, 0
	s_mov_b32 s73, -2
	v_mov_b64_e32 v[4:5], 0
	v_mov_b64_e32 v[66:67], 0
	v_mov_b64_e32 v[68:69], 0
	v_mov_b64_e32 v[10:11], 0
	v_mov_b64_e32 v[12:13], 0
	v_mov_b64_e32 v[70:71], 0
	v_mov_b64_e32 v[72:73], 0
	v_mov_b64_e32 v[18:19], 0
	v_mov_b64_e32 v[20:21], 0
	v_mov_b64_e32 v[82:83], 0
	v_mov_b64_e32 v[84:85], 0
	v_mov_b64_e32 v[26:27], 0
	v_mov_b64_e32 v[28:29], 0
	v_mov_b64_e32 v[100:101], 0
	v_mov_b64_e32 v[102:103], 0
	v_mov_b64_e32 v[6:7], 0
	v_mov_b64_e32 v[8:9], 0
	v_mov_b64_e32 v[74:75], 0
	v_mov_b64_e32 v[76:77], 0
	v_mov_b64_e32 v[14:15], 0
	v_mov_b64_e32 v[16:17], 0
	v_mov_b64_e32 v[78:79], 0
	v_mov_b64_e32 v[80:81], 0
	v_mov_b64_e32 v[22:23], 0
	v_mov_b64_e32 v[24:25], 0
	v_mov_b64_e32 v[88:89], 0
	v_mov_b64_e32 v[90:91], 0
	v_mov_b64_e32 v[30:31], 0
	v_mov_b64_e32 v[32:33], 0
	v_mov_b64_e32 v[120:121], 0
	v_mov_b64_e32 v[122:123], 0
	v_mov_b64_e32 v[34:35], 0
	v_mov_b64_e32 v[36:37], 0
	v_mov_b64_e32 v[94:95], 0
	v_mov_b64_e32 v[96:97], 0
	v_mov_b64_e32 v[42:43], 0
	v_mov_b64_e32 v[44:45], 0
	v_mov_b64_e32 v[128:129], 0
	v_mov_b64_e32 v[130:131], 0
	v_mov_b64_e32 v[50:51], 0
	v_mov_b64_e32 v[52:53], 0
	v_mov_b64_e32 v[136:137], 0
	v_mov_b64_e32 v[138:139], 0
	v_mov_b64_e32 v[58:59], 0
	v_mov_b64_e32 v[60:61], 0
	v_mov_b64_e32 v[144:145], 0
	v_mov_b64_e32 v[146:147], 0
	v_mov_b64_e32 v[38:39], 0
	v_mov_b64_e32 v[40:41], 0
	v_mov_b64_e32 v[124:125], 0
	v_mov_b64_e32 v[126:127], 0
	v_mov_b64_e32 v[46:47], 0
	v_mov_b64_e32 v[48:49], 0
	v_mov_b64_e32 v[132:133], 0
	v_mov_b64_e32 v[134:135], 0
	v_mov_b64_e32 v[54:55], 0
	v_mov_b64_e32 v[56:57], 0
	v_mov_b64_e32 v[140:141], 0
	v_mov_b64_e32 v[142:143], 0
	v_mov_b64_e32 v[62:63], 0
	v_mov_b64_e32 v[64:65], 0
	v_mov_b64_e32 v[148:149], 0
	v_mov_b64_e32 v[150:151], 0

; #define PG8_STAGE(bufoff, gbase, voff) do { _Pragma("unroll") for (int _i = 0; _i < 2; ++_i) \
;         __builtin_amdgcn_global_load_lds((const unsigned*)((const char*)(gbase) + (voff)[_i]), (PG8_LAS unsigned*)(lds + (bufoff) + ldsw + _i * 8192), 16, 0, 0); } while (0)
; #define PG8_LDA(dst, b, h) do { _Pragma("unroll") for (int m = 0; m < 4; ++m) _Pragma("unroll") for (int k = 0; k < 2; ++k) dst[m][k] = *(const PG8_LAS bf16x8*)(lds + PG8_SA(b, h) + aoff + m * 2048 + k * 1024); } while (0)
; #define PG8_LDB(dst, b, h) do { _Pragma("unroll") for (int n = 0; n < 2; ++n) _Pragma("unroll") for (int k = 0; k < 2; ++k) dst[n][k] = *(const PG8_LAS bf16x8*)(lds + PG8_SB(b, h) + boff + n * 2048 + k * 1024); } while (0)
; #define PG8_MMA(ai, bj, At, Bt) do { __builtin_amdgcn_s_setprio(1); _Pragma("unroll") for (int m = 0; m < 4; ++m) _Pragma("unroll") for (int n = 0; n < 2; ++n) _Pragma("unroll") for (int k = 0; k < 2; ++k) \
;         acc[ai][bj][m][n] = __builtin_amdgcn_mfma_f32_16x16x32_bf16(Bt[n][k], At[m][k], acc[ai][bj][m][n], 0, 0, 0); __builtin_amdgcn_s_setprio(0); } while (0)
; #define PG8_WAIT_V(n) asm volatile("s_waitcnt vmcnt(" #n ")" ::: "memory")
; #define PG8_WAIT_L(n) asm volatile("s_waitcnt lgkmcnt(" #n ")" ::: "memory")
; #define PG8_BAR __builtin_amdgcn_s_barrier()
; #define PG8_SCHED __builtin_amdgcn_sched_barrier(0)
; template <class Epi, class Sched, bool ALIGN_EPI = false, bool SP2 = false>
; __device__ __forceinline__ void gemm_phase(PG8_LAS unsigned char* lds, const Gemm g, const Sched& S, const Epi& E) {
;     ...
;             PG8_LDB(B0, 0, 0); PG8_LDB(B1, 0, 1); PG8_SCHED; PG8_LDA(At, 0, 0); PG8_STAGE(PG8_SA(1, 1), a1 + hstep, voffA);
;             PG8_WAIT_V(8); PG8_WAIT_L(0); PG8_BAR; PG8_MMA(0, 0, At, B0); PG8_MMA(0, 1, At, B1); PG8_BAR; PG8_SCHED;
;             PG8_LDA(At, 0, 1); PG8_STAGE(PG8_SB(0, 0), b2, voffB); PG8_STAGE(PG8_SB(0, 1), b2 + hstep, voffB); PG8_STAGE(PG8_SA(0, 0), a2, voffA);
;             PG8_WAIT_V(8); PG8_WAIT_L(0); PG8_BAR; PG8_MMA(1, 0, At, B0); PG8_MMA(1, 1, At, B1); PG8_BAR; PG8_SCHED;
.LBB0_1201:
	v_add_u32_e32 v164, s41, v150
	v_add_u32_e32 v180, s42, v150
	s_add_u32 s22, s12, s20
	ds_read_b128 v[152:155], v164
	ds_read_b128 v[156:159], v164 offset:1024
	ds_read_b128 v[160:163], v164 offset:2048
	ds_read_b128 v[164:167], v164 offset:3072
	ds_read_b128 v[168:171], v180
	ds_read_b128 v[172:175], v180 offset:1024
	ds_read_b128 v[176:179], v180 offset:2048
	ds_read_b128 v[180:183], v180 offset:3072
	s_addc_u32 s23, s13, s21
	s_add_u32 s22, s22, 0x100
	s_addc_u32 s23, s23, 0
	s_add_u32 s47, s2, s20
	s_addc_u32 s48, s3, s21
	s_cmpk_eq_i32 s20, 0x1500
	s_cselect_b32 s25, s19, s23
	s_cselect_b32 s24, s18, s22
	s_cselect_b32 s23, s7, s48
	s_cselect_b32 s22, s6, s47
	v_lshl_add_u64 v[200:201], v[146:147], 0, s[20:21]
	s_add_i32 m0, s33, 0xc000
	ds_read_b128 v[184:187], v151
	ds_read_b128 v[188:191], v151 offset:1024
	ds_read_b128 v[192:195], v151 offset:2048
	ds_read_b128 v[196:199], v151 offset:3072
	ds_read_b128 v[208:211], v151 offset:4096
	ds_read_b128 v[212:215], v151 offset:5120
	ds_read_b128 v[216:219], v151 offset:6144
	ds_read_b128 v[220:223], v151 offset:7168
	global_load_lds_dwordx4 v[200:201], off
	v_lshl_add_u64 v[200:201], v[148:149], 0, s[20:21]
	s_add_i32 m0, s33, 0xe000
	s_nop 0
	global_load_lds_dwordx4 v[200:201], off
	s_waitcnt vmcnt(8)
	s_waitcnt lgkmcnt(0)
	s_barrier
	s_setprio 1
	s_waitcnt lgkmcnt(0)
	v_mfma_f32_16x16x32_bf16 v[142:145], v[152:155], v[184:187], v[142:145]
	v_mfma_f32_16x16x32_bf16 v[138:141], v[160:163], v[184:187], v[138:141]
	v_mfma_f32_16x16x32_bf16 v[122:125], v[152:155], v[192:195], v[122:125]
	v_mfma_f32_16x16x32_bf16 v[118:121], v[160:163], v[192:195], v[118:121]
	v_mfma_f32_16x16x32_bf16 v[106:109], v[152:155], v[208:211], v[106:109]
	v_mfma_f32_16x16x32_bf16 v[102:105], v[160:163], v[208:211], v[102:105]
	v_mfma_f32_16x16x32_bf16 v[86:89], v[152:155], v[216:219], v[86:89]
	v_mfma_f32_16x16x32_bf16 v[82:85], v[160:163], v[216:219], v[82:85]
	v_mfma_f32_16x16x32_bf16 v[142:145], v[156:159], v[188:191], v[142:145]
	v_mfma_f32_16x16x32_bf16 v[138:141], v[164:167], v[188:191], v[138:141]
	v_mfma_f32_16x16x32_bf16 v[122:125], v[156:159], v[196:199], v[122:125]
	v_mfma_f32_16x16x32_bf16 v[118:121], v[164:167], v[196:199], v[118:121]
	v_mfma_f32_16x16x32_bf16 v[106:109], v[156:159], v[212:215], v[106:109]
	v_mfma_f32_16x16x32_bf16 v[102:105], v[164:167], v[212:215], v[102:105]
	v_mfma_f32_16x16x32_bf16 v[86:89], v[156:159], v[220:223], v[86:89]
	v_mfma_f32_16x16x32_bf16 v[82:85], v[164:167], v[220:223], v[82:85]
	s_setprio 0
	s_setprio 1
	v_mfma_f32_16x16x32_bf16 v[130:133], v[168:171], v[184:187], v[130:133]
	v_mfma_f32_16x16x32_bf16 v[126:129], v[176:179], v[184:187], v[126:129]
	v_mfma_f32_16x16x32_bf16 v[114:117], v[168:171], v[192:195], v[114:117]
	v_mfma_f32_16x16x32_bf16 v[110:113], v[176:179], v[192:195], v[110:113]
	v_mfma_f32_16x16x32_bf16 v[98:101], v[168:171], v[208:211], v[98:101]
	v_mfma_f32_16x16x32_bf16 v[90:93], v[176:179], v[208:211], v[90:93]
	v_mfma_f32_16x16x32_bf16 v[78:81], v[168:171], v[216:219], v[78:81]
	v_mfma_f32_16x16x32_bf16 v[74:77], v[176:179], v[216:219], v[74:77]
	v_mfma_f32_16x16x32_bf16 v[130:133], v[172:175], v[188:191], v[130:133]
	v_mfma_f32_16x16x32_bf16 v[126:129], v[180:183], v[188:191], v[126:129]
	v_mfma_f32_16x16x32_bf16 v[114:117], v[172:175], v[196:199], v[114:117]
	v_mfma_f32_16x16x32_bf16 v[110:113], v[180:183], v[196:199], v[110:113]
	v_mfma_f32_16x16x32_bf16 v[98:101], v[172:175], v[212:215], v[98:101]
	v_mfma_f32_16x16x32_bf16 v[90:93], v[180:183], v[212:215], v[90:93]
	v_mfma_f32_16x16x32_bf16 v[78:81], v[172:175], v[220:223], v[78:81]
	v_mfma_f32_16x16x32_bf16 v[74:77], v[180:183], v[220:223], v[74:77]
	s_setprio 0
	s_barrier
	s_add_i32 s47, s41, s31
	v_lshl_add_u64 v[200:201], s[22:23], 0, v[12:13]
	s_mov_b32 m0, s47
	ds_read_b128 v[184:187], v151 offset:16384
	ds_read_b128 v[188:191], v151 offset:17408
	ds_read_b128 v[192:195], v151 offset:18432
	ds_read_b128 v[196:199], v151 offset:19456
	ds_read_b128 v[208:211], v151 offset:20480
	ds_read_b128 v[212:215], v151 offset:21504
	ds_read_b128 v[216:219], v151 offset:22528
	ds_read_b128 v[220:223], v151 offset:23552
	global_load_lds_dwordx4 v[200:201], off
	s_add_i32 m0, s47, 0x2000
	s_add_u32 s48, s22, 0xb0000
	v_lshl_add_u64 v[204:205], s[22:23], 0, v[56:57]
	s_addc_u32 s49, s23, 0
	s_add_i32 s47, s42, s31
	global_load_lds_dwordx4 v[204:205], off
	v_lshl_add_u64 v[224:225], s[48:49], 0, v[12:13]
	s_mov_b32 m0, s47
	v_lshl_add_u64 v[226:227], s[24:25], 0, v[54:55]
	global_load_lds_dwordx4 v[224:225], off
	v_lshl_add_u64 v[224:225], s[48:49], 0, v[56:57]
	s_add_i32 m0, s47, 0x2000
	s_nop 0
	global_load_lds_dwordx4 v[224:225], off
	v_lshl_add_u64 v[224:225], s[24:25], 0, v[10:11]
	s_mov_b32 m0, s33
	s_nop 0
	global_load_lds_dwordx4 v[224:225], off
	s_mov_b32 m0, s34
	s_nop 0
	global_load_lds_dwordx4 v[226:227], off
	s_waitcnt vmcnt(8)
	s_waitcnt lgkmcnt(0)
	s_barrier
; #define PG8_STAGE(bufoff, gbase, voff) do { _Pragma("unroll") for (int _i = 0; _i < 2; ++_i) \
;         __builtin_amdgcn_global_load_lds((const unsigned*)((const char*)(gbase) + (voff)[_i]), (PG8_LAS unsigned*)(lds + (bufoff) + ldsw + _i * 8192), 16, 0, 0); } while (0)
; #define PG8_LDA(dst, b, h) do { _Pragma("unroll") for (int m = 0; m < 4; ++m) _Pragma("unroll") for (int k = 0; k < 2; ++k) dst[m][k] = *(const PG8_LAS bf16x8*)(lds + PG8_SA(b, h) + aoff + m * 2048 + k * 1024); } while (0)
; #define PG8_LDB(dst, b, h) do { _Pragma("unroll") for (int n = 0; n < 2; ++n) _Pragma("unroll") for (int k = 0; k < 2; ++k) dst[n][k] = *(const PG8_LAS bf16x8*)(lds + PG8_SB(b, h) + boff + n * 2048 + k * 1024); } while (0)
; #define PG8_MMA(ai, bj, At, Bt) do { __builtin_amdgcn_s_setprio(1); _Pragma("unroll") for (int m = 0; m < 4; ++m) _Pragma("unroll") for (int n = 0; n < 2; ++n) _Pragma("unroll") for (int k = 0; k < 2; ++k) \
;         acc[ai][bj][m][n] = __builtin_amdgcn_mfma_f32_16x16x32_bf16(Bt[n][k], At[m][k], acc[ai][bj][m][n], 0, 0, 0); __builtin_amdgcn_s_setprio(0); } while (0)
; #define PG8_WAIT_V(n) asm volatile("s_waitcnt vmcnt(" #n ")" ::: "memory")
; #define PG8_WAIT_L(n) asm volatile("s_waitcnt lgkmcnt(" #n ")" ::: "memory")
; #define PG8_BAR __builtin_amdgcn_s_barrier()
; #define PG8_SCHED __builtin_amdgcn_sched_barrier(0)
; template <class Epi, class Sched, bool ALIGN_EPI = false, bool SP2 = false>
; __device__ __forceinline__ void gemm_phase(PG8_LAS unsigned char* lds, const Gemm g, const Sched& S, const Epi& E) {
;     ...
;             PG8_WAIT_V(8); PG8_WAIT_L(0); PG8_BAR; PG8_MMA(1, 0, At, B0); PG8_MMA(1, 1, At, B1); PG8_BAR; PG8_SCHED;
;             PG8_LDB(B0, 1, 0); PG8_LDB(B1, 1, 1); PG8_SCHED; PG8_LDA(At, 1, 0); PG8_STAGE(PG8_SA(0, 1), a2 + hstep, voffA);
;             PG8_WAIT_V(8); PG8_WAIT_L(0); PG8_BAR; PG8_MMA(0, 0, At, B0); PG8_MMA(0, 1, At, B1); PG8_BAR; PG8_SCHED;
	s_setprio 1
	s_waitcnt lgkmcnt(0)
	v_mfma_f32_16x16x32_bf16 v[70:73], v[152:155], v[184:187], v[70:73]
	v_mfma_f32_16x16x32_bf16 v[66:69], v[160:163], v[184:187], v[66:69]
	v_mfma_f32_16x16x32_bf16 v[50:53], v[152:155], v[192:195], v[50:53]
	v_mfma_f32_16x16x32_bf16 v[46:49], v[160:163], v[192:195], v[46:49]
	v_mfma_f32_16x16x32_bf16 v[34:37], v[152:155], v[208:211], v[34:37]
	v_mfma_f32_16x16x32_bf16 v[30:33], v[160:163], v[208:211], v[30:33]
	v_mfma_f32_16x16x32_bf16 v[18:21], v[152:155], v[216:219], v[18:21]
	v_mfma_f32_16x16x32_bf16 v[14:17], v[160:163], v[216:219], v[14:17]
	v_mfma_f32_16x16x32_bf16 v[70:73], v[156:159], v[188:191], v[70:73]
	v_mfma_f32_16x16x32_bf16 v[66:69], v[164:167], v[188:191], v[66:69]
	v_mfma_f32_16x16x32_bf16 v[50:53], v[156:159], v[196:199], v[50:53]
	v_mfma_f32_16x16x32_bf16 v[46:49], v[164:167], v[196:199], v[46:49]
	v_mfma_f32_16x16x32_bf16 v[34:37], v[156:159], v[212:215], v[34:37]
	v_mfma_f32_16x16x32_bf16 v[30:33], v[164:167], v[212:215], v[30:33]
	v_mfma_f32_16x16x32_bf16 v[18:21], v[156:159], v[220:223], v[18:21]
	v_mfma_f32_16x16x32_bf16 v[14:17], v[164:167], v[220:223], v[14:17]
	s_setprio 0
	s_setprio 1
	v_mfma_f32_16x16x32_bf16 v[62:65], v[168:171], v[184:187], v[62:65]
	v_mfma_f32_16x16x32_bf16 v[58:61], v[176:179], v[184:187], v[58:61]
	v_mfma_f32_16x16x32_bf16 v[42:45], v[168:171], v[192:195], v[42:45]
	v_mfma_f32_16x16x32_bf16 v[38:41], v[176:179], v[192:195], v[38:41]
	v_mfma_f32_16x16x32_bf16 v[26:29], v[168:171], v[208:211], v[26:29]
	v_mfma_f32_16x16x32_bf16 v[22:25], v[176:179], v[208:211], v[22:25]
	v_mfma_f32_16x16x32_bf16 v[6:9], v[168:171], v[216:219], v[6:9]
	v_mfma_f32_16x16x32_bf16 v[2:5], v[176:179], v[216:219], v[2:5]
	v_mfma_f32_16x16x32_bf16 v[62:65], v[172:175], v[188:191], v[62:65]
	v_mfma_f32_16x16x32_bf16 v[58:61], v[180:183], v[188:191], v[58:61]
	v_mfma_f32_16x16x32_bf16 v[42:45], v[172:175], v[196:199], v[42:45]
	v_mfma_f32_16x16x32_bf16 v[38:41], v[180:183], v[196:199], v[38:41]
	v_mfma_f32_16x16x32_bf16 v[26:29], v[172:175], v[212:215], v[26:29]
	v_mfma_f32_16x16x32_bf16 v[22:25], v[180:183], v[212:215], v[22:25]
	v_mfma_f32_16x16x32_bf16 v[6:9], v[172:175], v[220:223], v[6:9]
	v_mfma_f32_16x16x32_bf16 v[2:5], v[180:183], v[220:223], v[2:5]
	s_setprio 0
	s_barrier
	s_add_i32 s47, 0, 0x18000
	s_add_i32 s48, 0, 0x1c000
	v_add_u32_e32 v164, s47, v150
	v_add_u32_e32 v180, s48, v150
	ds_read_b128 v[152:155], v164
	ds_read_b128 v[156:159], v164 offset:1024
	ds_read_b128 v[160:163], v164 offset:2048
	ds_read_b128 v[164:167], v164 offset:3072
	ds_read_b128 v[168:171], v180
	ds_read_b128 v[172:175], v180 offset:1024
	ds_read_b128 v[176:179], v180 offset:2048
	ds_read_b128 v[180:183], v180 offset:3072
	s_add_u32 s24, s24, 0xb0000
	s_addc_u32 s25, s25, 0
	s_mov_b32 m0, s35
	v_lshl_add_u64 v[228:229], s[24:25], 0, v[10:11]
	ds_read_b128 v[184:187], v151 offset:32768
	ds_read_b128 v[188:191], v151 offset:33792
	ds_read_b128 v[192:195], v151 offset:34816
	ds_read_b128 v[196:199], v151 offset:35840
	ds_read_b128 v[208:211], v151 offset:36864
	ds_read_b128 v[212:215], v151 offset:37888
	ds_read_b128 v[216:219], v151 offset:38912
	ds_read_b128 v[220:223], v151 offset:39936
	global_load_lds_dwordx4 v[228:229], off
	v_lshl_add_u64 v[228:229], s[24:25], 0, v[54:55]
	s_mov_b32 m0, s36
	s_nop 0
	global_load_lds_dwordx4 v[228:229], off
	s_waitcnt vmcnt(8)
	s_waitcnt lgkmcnt(0)
	s_barrier
	s_setprio 1
	s_waitcnt lgkmcnt(0)
	v_mfma_f32_16x16x32_bf16 v[142:145], v[152:155], v[184:187], v[142:145]
	v_mfma_f32_16x16x32_bf16 v[138:141], v[160:163], v[184:187], v[138:141]
	v_mfma_f32_16x16x32_bf16 v[122:125], v[152:155], v[192:195], v[122:125]
	v_mfma_f32_16x16x32_bf16 v[118:121], v[160:163], v[192:195], v[118:121]
	v_mfma_f32_16x16x32_bf16 v[106:109], v[152:155], v[208:211], v[106:109]
	v_mfma_f32_16x16x32_bf16 v[102:105], v[160:163], v[208:211], v[102:105]
	v_mfma_f32_16x16x32_bf16 v[86:89], v[152:155], v[216:219], v[86:89]
	v_mfma_f32_16x16x32_bf16 v[82:85], v[160:163], v[216:219], v[82:85]
	v_mfma_f32_16x16x32_bf16 v[142:145], v[156:159], v[188:191], v[142:145]
	v_mfma_f32_16x16x32_bf16 v[138:141], v[164:167], v[188:191], v[138:141]
	v_mfma_f32_16x16x32_bf16 v[122:125], v[156:159], v[196:199], v[122:125]
	v_mfma_f32_16x16x32_bf16 v[118:121], v[164:167], v[196:199], v[118:121]
	v_mfma_f32_16x16x32_bf16 v[106:109], v[156:159], v[212:215], v[106:109]
	v_mfma_f32_16x16x32_bf16 v[102:105], v[164:167], v[212:215], v[102:105]
	v_mfma_f32_16x16x32_bf16 v[86:89], v[156:159], v[220:223], v[86:89]
	v_mfma_f32_16x16x32_bf16 v[82:85], v[164:167], v[220:223], v[82:85]
	s_setprio 0
	s_setprio 1
	v_mfma_f32_16x16x32_bf16 v[130:133], v[168:171], v[184:187], v[130:133]
	v_mfma_f32_16x16x32_bf16 v[126:129], v[176:179], v[184:187], v[126:129]
	v_mfma_f32_16x16x32_bf16 v[114:117], v[168:171], v[192:195], v[114:117]
	v_mfma_f32_16x16x32_bf16 v[110:113], v[176:179], v[192:195], v[110:113]
	v_mfma_f32_16x16x32_bf16 v[98:101], v[168:171], v[208:211], v[98:101]
	v_mfma_f32_16x16x32_bf16 v[90:93], v[176:179], v[208:211], v[90:93]
	v_mfma_f32_16x16x32_bf16 v[78:81], v[168:171], v[216:219], v[78:81]
	v_mfma_f32_16x16x32_bf16 v[74:77], v[176:179], v[216:219], v[74:77]
	v_mfma_f32_16x16x32_bf16 v[130:133], v[172:175], v[188:191], v[130:133]
	v_mfma_f32_16x16x32_bf16 v[126:129], v[180:183], v[188:191], v[126:129]
	v_mfma_f32_16x16x32_bf16 v[114:117], v[172:175], v[196:199], v[114:117]
	v_mfma_f32_16x16x32_bf16 v[110:113], v[180:183], v[196:199], v[110:113]
	v_mfma_f32_16x16x32_bf16 v[98:101], v[172:175], v[212:215], v[98:101]
	v_mfma_f32_16x16x32_bf16 v[90:93], v[180:183], v[212:215], v[90:93]
	v_mfma_f32_16x16x32_bf16 v[78:81], v[172:175], v[220:223], v[78:81]
	v_mfma_f32_16x16x32_bf16 v[74:77], v[180:183], v[220:223], v[74:77]
	s_setprio 0
	s_barrier
; #define PG8_STAGE(bufoff, gbase, voff) do { _Pragma("unroll") for (int _i = 0; _i < 2; ++_i) \
;         __builtin_amdgcn_global_load_lds((const unsigned*)((const char*)(gbase) + (voff)[_i]), (PG8_LAS unsigned*)(lds + (bufoff) + ldsw + _i * 8192), 16, 0, 0); } while (0)
; #define PG8_LDA(dst, b, h) do { _Pragma("unroll") for (int m = 0; m < 4; ++m) _Pragma("unroll") for (int k = 0; k < 2; ++k) dst[m][k] = *(const PG8_LAS bf16x8*)(lds + PG8_SA(b, h) + aoff + m * 2048 + k * 1024); } while (0)
; #define PG8_MMA(ai, bj, At, Bt) do { __builtin_amdgcn_s_setprio(1); _Pragma("unroll") for (int m = 0; m < 4; ++m) _Pragma("unroll") for (int n = 0; n < 2; ++n) _Pragma("unroll") for (int k = 0; k < 2; ++k) \
;         acc[ai][bj][m][n] = __builtin_amdgcn_mfma_f32_16x16x32_bf16(Bt[n][k], At[m][k], acc[ai][bj][m][n], 0, 0, 0); __builtin_amdgcn_s_setprio(0); } while (0)
; #define PG8_WAIT_V(n) asm volatile("s_waitcnt vmcnt(" #n ")" ::: "memory")
; #define PG8_WAIT_L(n) asm volatile("s_waitcnt lgkmcnt(" #n ")" ::: "memory")
; #define PG8_BAR __builtin_amdgcn_s_barrier()
; #define PG8_SCHED __builtin_amdgcn_sched_barrier(0)
; template <class Epi, class Sched, bool ALIGN_EPI = false, bool SP2 = false>
; __device__ __forceinline__ void gemm_phase(PG8_LAS unsigned char* lds, const Gemm g, const Sched& S, const Epi& E) {
;     ...
;             PG8_LDA(At, 1, 1); PG8_STAGE(PG8_SB(1, 0), b3, voffB); PG8_STAGE(PG8_SB(1, 1), b3 + hstep, voffB); PG8_STAGE(PG8_SA(1, 0), a3, voffA);
;             PG8_WAIT_V(8); PG8_WAIT_L(0); PG8_BAR; PG8_MMA(1, 0, At, B0); PG8_MMA(1, 1, At, B1); PG8_BAR; PG8_SCHED;
;     ...
; #pragma unroll
;         for (int a = 0; a < 2; ++a)
; #pragma unroll
;             for (int b = 0; b < 2; ++b)
; #pragma unroll
;                 for (int m = 0; m < 4; ++m)
; #pragma unroll
;                     for (int n = 0; n < 2; ++n) acc[a][b][m][n] = (f32x4){0.f, 0.f, 0.f, 0.f};
	s_add_i32 s24, s47, s31
	v_lshl_add_u64 v[200:201], v[200:201], 0, s[16:17]
	s_mov_b32 m0, s24
	ds_read_b128 v[184:187], v151 offset:49152
	ds_read_b128 v[188:191], v151 offset:50176
	ds_read_b128 v[192:195], v151 offset:51200
	ds_read_b128 v[196:199], v151 offset:52224
	ds_read_b128 v[208:211], v151 offset:53248
	ds_read_b128 v[212:215], v151 offset:54272
	ds_read_b128 v[216:219], v151 offset:55296
	ds_read_b128 v[220:223], v151 offset:56320
	global_load_lds_dwordx4 v[200:201], off
	s_add_i32 m0, s24, 0x2000
	s_add_u32 s22, s22, 0xb0080
	v_lshl_add_u64 v[200:201], v[204:205], 0, s[16:17]
	s_addc_u32 s23, s23, 0
	s_add_i32 s24, s48, s31
	global_load_lds_dwordx4 v[200:201], off
	v_lshl_add_u64 v[200:201], s[22:23], 0, v[12:13]
	s_mov_b32 m0, s24
	s_nop 0
	global_load_lds_dwordx4 v[200:201], off
	v_lshl_add_u64 v[200:201], s[22:23], 0, v[56:57]
	s_add_i32 m0, s24, 0x2000
	s_nop 0
	global_load_lds_dwordx4 v[200:201], off
	v_lshl_add_u64 v[200:201], v[224:225], 0, s[16:17]
	s_mov_b32 m0, s38
	s_nop 0
	global_load_lds_dwordx4 v[200:201], off
	v_lshl_add_u64 v[200:201], v[226:227], 0, s[16:17]
	s_mov_b32 m0, s39
	s_nop 0
	global_load_lds_dwordx4 v[200:201], off
	s_waitcnt vmcnt(8)
	s_waitcnt lgkmcnt(0)
	s_barrier
	s_setprio 1
	s_waitcnt lgkmcnt(0)
	v_mfma_f32_16x16x32_bf16 v[70:73], v[152:155], v[184:187], v[70:73]
	v_mfma_f32_16x16x32_bf16 v[66:69], v[160:163], v[184:187], v[66:69]
	v_mfma_f32_16x16x32_bf16 v[50:53], v[152:155], v[192:195], v[50:53]
	v_mfma_f32_16x16x32_bf16 v[46:49], v[160:163], v[192:195], v[46:49]
	v_mfma_f32_16x16x32_bf16 v[34:37], v[152:155], v[208:211], v[34:37]
	v_mfma_f32_16x16x32_bf16 v[30:33], v[160:163], v[208:211], v[30:33]
	v_mfma_f32_16x16x32_bf16 v[18:21], v[152:155], v[216:219], v[18:21]
	v_mfma_f32_16x16x32_bf16 v[14:17], v[160:163], v[216:219], v[14:17]
	v_mfma_f32_16x16x32_bf16 v[70:73], v[156:159], v[188:191], v[70:73]
	v_mfma_f32_16x16x32_bf16 v[66:69], v[164:167], v[188:191], v[66:69]
	v_mfma_f32_16x16x32_bf16 v[50:53], v[156:159], v[196:199], v[50:53]
	v_mfma_f32_16x16x32_bf16 v[46:49], v[164:167], v[196:199], v[46:49]
	v_mfma_f32_16x16x32_bf16 v[34:37], v[156:159], v[212:215], v[34:37]
	v_mfma_f32_16x16x32_bf16 v[30:33], v[164:167], v[212:215], v[30:33]
	v_mfma_f32_16x16x32_bf16 v[18:21], v[156:159], v[220:223], v[18:21]
	v_mfma_f32_16x16x32_bf16 v[14:17], v[164:167], v[220:223], v[14:17]
	s_setprio 0
	s_setprio 1
	v_mfma_f32_16x16x32_bf16 v[62:65], v[168:171], v[184:187], v[62:65]
	v_mfma_f32_16x16x32_bf16 v[58:61], v[176:179], v[184:187], v[58:61]
	v_mfma_f32_16x16x32_bf16 v[42:45], v[168:171], v[192:195], v[42:45]
	v_mfma_f32_16x16x32_bf16 v[38:41], v[176:179], v[192:195], v[38:41]
	v_mfma_f32_16x16x32_bf16 v[26:29], v[168:171], v[208:211], v[26:29]
	v_mfma_f32_16x16x32_bf16 v[22:25], v[176:179], v[208:211], v[22:25]
	v_mfma_f32_16x16x32_bf16 v[6:9], v[168:171], v[216:219], v[6:9]
	v_mfma_f32_16x16x32_bf16 v[2:5], v[176:179], v[216:219], v[2:5]
	v_mfma_f32_16x16x32_bf16 v[62:65], v[172:175], v[188:191], v[62:65]
	v_mfma_f32_16x16x32_bf16 v[58:61], v[180:183], v[188:191], v[58:61]
	v_mfma_f32_16x16x32_bf16 v[42:45], v[172:175], v[196:199], v[42:45]
	v_mfma_f32_16x16x32_bf16 v[38:41], v[180:183], v[196:199], v[38:41]
	v_mfma_f32_16x16x32_bf16 v[26:29], v[172:175], v[212:215], v[26:29]
	v_mfma_f32_16x16x32_bf16 v[22:25], v[180:183], v[212:215], v[22:25]
	v_mfma_f32_16x16x32_bf16 v[6:9], v[172:175], v[220:223], v[6:9]
	v_mfma_f32_16x16x32_bf16 v[2:5], v[180:183], v[220:223], v[2:5]
	s_setprio 0
	s_barrier
	s_add_i32 s46, s46, 2
	s_add_u32 s20, s20, 0x100
	s_addc_u32 s21, s21, 0
	s_cmp_gt_u32 s46, 41
	s_cbranch_scc0 .LBB0_1201
	s_add_u32 s20, s2, 0xffffff00
	s_addc_u32 s21, s3, -1
	s_and_b64 vcc, exec, s[4:5]
	s_cbranch_vccnz .LBB0_1188
	v_mov_b64_e32 v[2:3], 0
	s_mov_b32 s10, s43
	s_mov_b32 s28, s44
	s_mov_b64 s[12:13], s[18:19]
	s_mov_b32 s40, s45
	v_mov_b64_e32 v[4:5], 0
	v_mov_b64_e32 v[6:7], 0
	v_mov_b64_e32 v[8:9], 0
	v_mov_b64_e32 v[22:23], 0
	v_mov_b64_e32 v[24:25], 0
	v_mov_b64_e32 v[26:27], 0
	v_mov_b64_e32 v[28:29], 0
	v_mov_b64_e32 v[38:39], 0
	v_mov_b64_e32 v[40:41], 0
	v_mov_b64_e32 v[42:43], 0
	v_mov_b64_e32 v[44:45], 0
	v_mov_b64_e32 v[58:59], 0
	v_mov_b64_e32 v[60:61], 0
	v_mov_b64_e32 v[62:63], 0
	v_mov_b64_e32 v[64:65], 0
	v_mov_b64_e32 v[14:15], 0
	v_mov_b64_e32 v[16:17], 0
	v_mov_b64_e32 v[18:19], 0
	v_mov_b64_e32 v[20:21], 0
	v_mov_b64_e32 v[30:31], 0
	v_mov_b64_e32 v[32:33], 0
	v_mov_b64_e32 v[34:35], 0
	v_mov_b64_e32 v[36:37], 0
	v_mov_b64_e32 v[46:47], 0
	v_mov_b64_e32 v[48:49], 0
	v_mov_b64_e32 v[50:51], 0
	v_mov_b64_e32 v[52:53], 0
	v_mov_b64_e32 v[66:67], 0
	v_mov_b64_e32 v[68:69], 0
	v_mov_b64_e32 v[70:71], 0
	v_mov_b64_e32 v[72:73], 0
	v_mov_b64_e32 v[74:75], 0
	v_mov_b64_e32 v[76:77], 0
	v_mov_b64_e32 v[78:79], 0
	v_mov_b64_e32 v[80:81], 0
	v_mov_b64_e32 v[90:91], 0
	v_mov_b64_e32 v[92:93], 0
	v_mov_b64_e32 v[98:99], 0
	v_mov_b64_e32 v[100:101], 0
	v_mov_b64_e32 v[110:111], 0
	v_mov_b64_e32 v[112:113], 0
	v_mov_b64_e32 v[114:115], 0
	v_mov_b64_e32 v[116:117], 0
	v_mov_b64_e32 v[126:127], 0
	v_mov_b64_e32 v[128:129], 0
	v_mov_b64_e32 v[130:131], 0
	v_mov_b64_e32 v[132:133], 0
	v_mov_b64_e32 v[82:83], 0
	v_mov_b64_e32 v[84:85], 0
	v_mov_b64_e32 v[86:87], 0
	v_mov_b64_e32 v[88:89], 0
	v_mov_b64_e32 v[102:103], 0
	v_mov_b64_e32 v[104:105], 0
	v_mov_b64_e32 v[106:107], 0
	v_mov_b64_e32 v[108:109], 0
	v_mov_b64_e32 v[118:119], 0
	v_mov_b64_e32 v[120:121], 0
	v_mov_b64_e32 v[122:123], 0
	v_mov_b64_e32 v[124:125], 0
	v_mov_b64_e32 v[138:139], 0
	v_mov_b64_e32 v[140:141], 0
	v_mov_b64_e32 v[142:143], 0
	v_mov_b64_e32 v[144:145], 0
	s_andn2_b64 vcc, exec, s[0:1]
	s_cbranch_vccnz .LBB0_1189
